# adds: 9600 gate/up transposition items of layer l+1 moved into the 240 idle CUs of layer l out-projection GEMM tail
# speedup vs baseline: 1.0170x; 1.0014x over previous
; #define LAS __attribute__((address_space(3)))
; #define GAS __attribute__((address_space(1)))
; DEV int readfirstlane_i(int v) { return __builtin_amdgcn_readfirstlane(v); }
; __global__ void __launch_bounds__(NTHREADS, 2) mega_fwd(Args args) {
;     ...
;     Frame F;
;     F.in = args.in; F.out = (GAS float*)args.out; F.ws = (GAS unsigned char*)args.ws; F.lds = lds;
;     F.tid = threadIdx.x; F.lane = F.tid & 63; F.wave = readfirstlane_i(F.tid >> 6); F.G = gridDim.x; F.bid = blockIdx.x;
;     F.gw = F.bid * NWAVES + F.wave; F.NGW = F.G * NWAVES;
;     for (int u = F.tid; u < (LDS_BYTES - LDS_MISC) / 4; u += NTHREADS) ((LAS unsigned*)(lds + LDS_MISC))[u] = 0u;
;     __syncthreads();
;     XcdBarrier bar = xcd_barrier_post((unsigned*)(F.ws + WS_CTL), (volatile LAS unsigned*)(lds + LDS_MISC), F.wave);
_Z8mega_fwd4Args:
	s_load_dwordx2 s[100:101], s[0:1], 0x68
	s_waitcnt lgkmcnt(0)
	v_writelane_b32 v255, s100, 49
	v_writelane_b32 v255, s101, 50
	s_load_dwordx2 s[100:101], s[0:1], 0x128
	s_waitcnt lgkmcnt(0)
	v_writelane_b32 v255, s100, 53
	v_writelane_b32 v255, s101, 54
	s_load_dwordx2 s[100:101], s[0:1], 0x58
	s_waitcnt lgkmcnt(0)
	v_writelane_b32 v255, s100, 55
	v_writelane_b32 v255, s101, 56
	s_load_dwordx2 s[100:101], s[0:1], 0x60
	s_waitcnt lgkmcnt(0)
	v_writelane_b32 v255, s100, 57
	v_writelane_b32 v255, s101, 58
	s_load_dword s100, s[0:1], 0x130
	s_waitcnt lgkmcnt(0)
	v_writelane_b32 v255, s100, 51
	v_writelane_b32 v255, s2, 48
	s_mov_b32 s100, 0
	v_writelane_b32 v255, s100, 52
	s_nop 0
	s_load_dwordx4 s[4:7], s[0:1], 0x120
	s_load_dwordx8 s[8:15], s[0:1], 0x100
	s_mov_b32 s24, s2
	s_movk_i32 s2, 0x80
	v_cmp_gt_u32_e32 vcc, s2, v0
	s_waitcnt lgkmcnt(0)
	v_writelane_b32 v251, s4, 0
	s_nop 1
	v_writelane_b32 v251, s5, 1
	v_writelane_b32 v251, s6, 2
	v_writelane_b32 v251, s7, 3
	v_readfirstlane_b32 s6, v0
	s_and_saveexec_b64 s[2:3], vcc
	v_lshl_add_u32 v0, v0, 2, 0
	v_add_u32_e32 v0, 0x27e00, v0
	v_mov_b32_e32 v1, 0
	ds_write_b32 v0, v1
	v_writelane_b32 v251, s8, 4
	s_nop 1
	v_writelane_b32 v251, s9, 5
	v_writelane_b32 v251, s10, 6
	v_writelane_b32 v251, s11, 7
	v_writelane_b32 v251, s12, 8
	v_writelane_b32 v251, s13, 9
	v_writelane_b32 v251, s14, 10
	v_writelane_b32 v251, s15, 11
	s_or_b64 exec, exec, s[2:3]
	s_load_dword s96, s[0:1], 0x130
	s_load_dwordx16 s[44:59], s[0:1], 0x40
	s_load_dwordx16 s[8:23], s[0:1], 0x80
	s_waitcnt lgkmcnt(0)
	s_barrier
	s_getreg_b32 s2, hwreg(HW_REG_XCC_ID, 0, 4)
	v_writelane_b32 v251, s8, 12
	s_and_b32 s2, s2, 15
	s_cmp_gt_u32 s6, 63
	v_writelane_b32 v251, s9, 13
	v_writelane_b32 v251, s10, 14
	v_writelane_b32 v251, s11, 15
	v_writelane_b32 v251, s12, 16
	v_writelane_b32 v251, s13, 17
	v_writelane_b32 v251, s14, 18
	v_writelane_b32 v251, s15, 19
	v_writelane_b32 v251, s16, 20
	v_writelane_b32 v251, s17, 21
	v_writelane_b32 v251, s18, 22
	v_writelane_b32 v251, s19, 23
	v_writelane_b32 v251, s20, 24
	v_writelane_b32 v251, s21, 25
	v_writelane_b32 v251, s22, 26
	v_writelane_b32 v251, s23, 27
	v_writelane_b32 v251, s2, 28
	v_mbcnt_lo_u32_b32 v0, -1, 0
	s_cbranch_scc1 .LBB0_7
	v_mbcnt_hi_u32_b32 v1, -1, v0
	v_cmp_eq_u32_e32 vcc, 0, v1
	s_and_saveexec_b64 s[2:3], vcc
	s_cbranch_execz .LBB0_6
	s_mov_b64 s[4:5], exec
	v_mbcnt_lo_u32_b32 v1, s4, 0
	v_mbcnt_hi_u32_b32 v1, s5, v1
	v_cmp_eq_u32_e32 vcc, 0, v1
	s_and_b64 s[8:9], exec, vcc
	s_mov_b64 exec, s[8:9]
	s_cbranch_execz .LBB0_6
	s_load_dwordx4 s[8:11], s[0:1], 0x120
	v_readlane_b32 s7, v251, 28
	s_lshl_b32 s7, s7, 8
	s_bcnt1_i32_b64 s4, s[4:5]
	v_mov_b32_e32 v1, s7
	v_mov_b32_e32 v2, s4
	s_waitcnt lgkmcnt(0)
	global_atomic_add v1, v2, s[10:11] offset:1024

; #define LAS __attribute__((address_space(3)))
; #define NT_LOAD(p) __builtin_nontemporal_load(p)
; DEV void tr_item(const float* W, int ldw, int col0, int k0, bf16_t* WT, int K, int row0, LAS float* scr, int lane) {
; #pragma unroll 8
;     for (int i = 0; i < 32; ++i) { const int kk = 2 * i + (lane >> 5); scr[kk * 33 + (lane & 31)] = NT_LOAD(&W[(size_t)(k0 + kk) * ldw + col0 + (lane & 31)]); }
; DEV void phase_prologue_a(const Frame& F0) {
;     ...
;         constexpr int GU_NB = 2 * FF / 32, GU_ITEMS = 16 * GU_NB;
;         for (int it = F.gw; it < NE * GU_ITEMS; it += F.NGW) { const int e = it / GU_ITEMS, r = it % GU_ITEMS, kb = r / GU_NB, nb = r % GU_NB; const int d0 = 32 * nb, j = d0 >> 8, w = d0 & 255;
;             const float* src = (w < 128 ? GIN(I_WGATE) : GIN(I_WUP)) + ((size_t)l * NE + e) * 1024 * FF;
;             tr_item(src, FF, 128 * j + (w & 127), 64 * kb, (bf16_t*)(F.ws + WS_WGU) + ((size_t)l * NE + e) * 2 * FF * 1024, 1024, d0, scr, F.lane); }
.LBB0_24:
	s_andn2_b64 vcc, exec, s[10:11]
	s_cbranch_vccnz .LBB0_29
	s_lshl_b64 s[20:21], s[2:3], 27
	s_mov_b32 s28, s31
	s_cmp_eq_u32 s14, 0
	s_cbranch_scc1 .Lpro_gu_all
	v_readlane_b32 s100, v255, 51
	s_cmp_lg_u32 s100, 0x100
	s_cbranch_scc1 .Lpro_gu_all
	s_addk_i32 s28, 0x2580
.Lpro_gu_all:
	s_mov_b64 s[40:41], 0x20000
	s_mov_b64 s[42:43], 0x4000
	v_add_u32_e32 v100, 0x400, v42
	v_add_u32_e32 v101, 0x840, v42
	v_add_u32_e32 v102, 0xc40, v42
	v_add_u32_e32 v103, 0x1080, v42
	v_add_u32_e32 v104, 0x1480, v42
	v_add_u32_e32 v105, 0x18c0, v42
	v_add_u32_e32 v106, 0x1cc0, v42
	s_ashr_i32 s22, s28, 31
	s_lshr_b32 s22, s22, 21
	s_add_i32 s23, s28, s22
	s_ashr_i32 s22, s23, 11
	s_and_b32 s23, s23, 0xf800
	s_sub_i32 s23, s28, s23
	s_sext_i32_i16 s24, s23
	s_lshr_b32 s24, s24, 24
	s_and_b32 s24, s24, 0x7f
	s_add_i32 s24, s23, s24
	s_sext_i32_i16 s25, s24
	s_and_b32 s24, s24, 0xff80
	s_sub_i32 s23, s23, s24
	s_sext_i32_i16 s24, s23
	s_ashr_i32 s25, s25, 7
	s_lshl_b32 s29, s24, 5
	s_bitcmp0_b32 s23, 2
	s_cselect_b32 s27, s51, s53
	s_cselect_b32 s26, s50, s52
	s_lshl_b32 s24, s24, 4
	s_and_b32 s24, s24, 0xffffff80
	s_and_b32 s37, s29, 0x60
	s_or_b32 s38, s24, s37
	s_ashr_i32 s23, s22, 31
	s_ashr_i32 s39, s38, 31
	s_lshl_b64 s[22:23], s[22:23], 23
	s_lshl_b32 s24, s25, 6
	v_lshl_add_u64 v[36:37], s[26:27], 0, v[20:21]
	s_lshl_b64 s[26:27], s[38:39], 2
	s_add_u32 s26, s26, s22
	v_add_u32_e32 v22, s24, v45
	s_addc_u32 s27, s27, s23
	v_add_u32_e32 v24, s24, v46
	v_add_u32_e32 v26, s24, v47
	v_add_u32_e32 v28, s24, v48
	v_add_u32_e32 v30, s24, v49
	v_add_u32_e32 v32, s24, v43
	v_add_u32_e32 v34, s24, v44
	s_ashr_i32 s25, s24, 31
	v_ashrrev_i32_e32 v23, 31, v22
	v_ashrrev_i32_e32 v25, 31, v24
	v_ashrrev_i32_e32 v27, 31, v26
	v_ashrrev_i32_e32 v29, 31, v28
	v_ashrrev_i32_e32 v31, 31, v30
	v_ashrrev_i32_e32 v33, 31, v32
	v_ashrrev_i32_e32 v35, 31, v34
	v_lshl_add_u64 v[52:53], v[2:3], 0, s[24:25]
	v_lshlrev_b64 v[22:23], 13, v[22:23]
	v_lshlrev_b64 v[24:25], 13, v[24:25]
	v_lshlrev_b64 v[26:27], 13, v[26:27]
	v_lshlrev_b64 v[28:29], 13, v[28:29]
	v_lshlrev_b64 v[30:31], 13, v[30:31]
	v_lshlrev_b64 v[32:33], 13, v[32:33]
	v_lshlrev_b64 v[34:35], 13, v[34:35]
	v_lshlrev_b64 v[52:53], 13, v[52:53]
	v_lshl_add_u64 v[22:23], s[26:27], 0, v[22:23]
	v_lshl_add_u64 v[24:25], s[26:27], 0, v[24:25]
	v_lshl_add_u64 v[26:27], s[26:27], 0, v[26:27]
	v_lshl_add_u64 v[28:29], s[26:27], 0, v[28:29]
	v_lshl_add_u64 v[30:31], s[26:27], 0, v[30:31]
	v_lshl_add_u64 v[32:33], s[26:27], 0, v[32:33]
	v_lshl_add_u64 v[34:35], s[26:27], 0, v[34:35]
	v_lshl_add_u64 v[52:53], s[26:27], 0, v[52:53]
	v_lshl_add_u64 v[22:23], v[36:37], 0, v[22:23]
	v_lshl_add_u64 v[24:25], v[36:37], 0, v[24:25]
	v_lshl_add_u64 v[26:27], v[36:37], 0, v[26:27]
	v_lshl_add_u64 v[28:29], v[36:37], 0, v[28:29]
	v_lshl_add_u64 v[30:31], v[36:37], 0, v[30:31]
	v_lshl_add_u64 v[32:33], v[36:37], 0, v[32:33]
	v_lshl_add_u64 v[34:35], v[36:37], 0, v[34:35]
	v_lshl_add_u64 v[36:37], v[36:37], 0, v[52:53]
	global_load_dword v68, v[36:37], off nt
	global_load_dword v69, v[34:35], off nt
	global_load_dword v70, v[32:33], off nt
	global_load_dword v71, v[30:31], off nt
	global_load_dword v72, v[28:29], off nt
	global_load_dword v73, v[26:27], off nt
	global_load_dword v74, v[24:25], off nt
	global_load_dword v75, v[22:23], off nt
	v_lshl_add_u64 v[36:37], v[36:37], 0, s[40:41]
	v_lshl_add_u64 v[34:35], v[34:35], 0, s[40:41]
	v_lshl_add_u64 v[32:33], v[32:33], 0, s[40:41]
	v_lshl_add_u64 v[30:31], v[30:31], 0, s[40:41]
	v_lshl_add_u64 v[28:29], v[28:29], 0, s[40:41]
	v_lshl_add_u64 v[26:27], v[26:27], 0, s[40:41]
	v_lshl_add_u64 v[24:25], v[24:25], 0, s[40:41]
	v_lshl_add_u64 v[22:23], v[22:23], 0, s[40:41]
	global_load_dword v76, v[36:37], off nt
	global_load_dword v77, v[34:35], off nt
	global_load_dword v78, v[32:33], off nt
	global_load_dword v79, v[30:31], off nt
	global_load_dword v80, v[28:29], off nt
	global_load_dword v81, v[26:27], off nt
	global_load_dword v82, v[24:25], off nt
	global_load_dword v83, v[22:23], off nt
	v_lshl_add_u64 v[36:37], v[36:37], 0, s[40:41]
	v_lshl_add_u64 v[34:35], v[34:35], 0, s[40:41]
	v_lshl_add_u64 v[32:33], v[32:33], 0, s[40:41]
	v_lshl_add_u64 v[30:31], v[30:31], 0, s[40:41]
	v_lshl_add_u64 v[28:29], v[28:29], 0, s[40:41]
	v_lshl_add_u64 v[26:27], v[26:27], 0, s[40:41]
	v_lshl_add_u64 v[24:25], v[24:25], 0, s[40:41]
	v_lshl_add_u64 v[22:23], v[22:23], 0, s[40:41]
	global_load_dword v84, v[36:37], off nt
	global_load_dword v85, v[34:35], off nt
	global_load_dword v86, v[32:33], off nt
	global_load_dword v87, v[30:31], off nt
	global_load_dword v88, v[28:29], off nt
	global_load_dword v89, v[26:27], off nt
	global_load_dword v90, v[24:25], off nt
	global_load_dword v91, v[22:23], off nt
	v_lshl_add_u64 v[36:37], v[36:37], 0, s[40:41]
	v_lshl_add_u64 v[34:35], v[34:35], 0, s[40:41]
	v_lshl_add_u64 v[32:33], v[32:33], 0, s[40:41]
	v_lshl_add_u64 v[30:31], v[30:31], 0, s[40:41]
	v_lshl_add_u64 v[28:29], v[28:29], 0, s[40:41]
	v_lshl_add_u64 v[26:27], v[26:27], 0, s[40:41]
	v_lshl_add_u64 v[24:25], v[24:25], 0, s[40:41]
	v_lshl_add_u64 v[22:23], v[22:23], 0, s[40:41]
	global_load_dword v92, v[36:37], off nt
	global_load_dword v93, v[34:35], off nt
	global_load_dword v94, v[32:33], off nt
	global_load_dword v95, v[30:31], off nt
	global_load_dword v96, v[28:29], off nt
	global_load_dword v97, v[26:27], off nt
	global_load_dword v98, v[24:25], off nt
	global_load_dword v99, v[22:23], off nt
	s_waitcnt vmcnt(0)

; #define LAS __attribute__((address_space(3)))
; #define NT_LOAD(p) __builtin_nontemporal_load(p)
; DEV void tr_item(const float* W, int ldw, int col0, int k0, bf16_t* WT, int K, int row0, LAS float* scr, int lane) {
; #pragma unroll 8
;     for (int i = 0; i < 32; ++i) { const int kk = 2 * i + (lane >> 5); scr[kk * 33 + (lane & 31)] = NT_LOAD(&W[(size_t)(k0 + kk) * ldw + col0 + (lane & 31)]); }
; DEV void phase_prologue_a(const Frame& F0) {
;     ...
;         constexpr int GU_NB = 2 * FF / 32, GU_ITEMS = 16 * GU_NB;
;         for (int it = F.gw; it < NE * GU_ITEMS; it += F.NGW) { const int e = it / GU_ITEMS, r = it % GU_ITEMS, kb = r / GU_NB, nb = r % GU_NB; const int d0 = 32 * nb, j = d0 >> 8, w = d0 & 255;
;             const float* src = (w < 128 ? GIN(I_WGATE) : GIN(I_WUP)) + ((size_t)l * NE + e) * 1024 * FF;
;             tr_item(src, FF, 128 * j + (w & 127), 64 * kb, (bf16_t*)(F.ws + WS_WGU) + ((size_t)l * NE + e) * 2 * FF * 1024, 1024, d0, scr, F.lane); }
.LBB0_1332:
	s_waitcnt vmcnt(0)
	s_barrier
	v_readlane_b32 s3, v255, 52
	s_add_i32 s0, s3, 1
	s_cmp_gt_u32 s0, 3
	s_cbranch_scc1 .Lsg_done
	v_readlane_b32 s2, v255, 51
	s_cmp_lg_u32 s2, 0x100
	s_cbranch_scc1 .Lsg_done
	v_readlane_b32 s2, v255, 48
	s_cmp_lt_u32 s2, 16
	s_cbranch_scc1 .Lsg_done
	v_readlane_b32 s3, v251, 29
	s_sub_i32 s2, s2, 16
	s_lshl_b32 s2, s2, 3
	s_add_i32 s2, s2, s3
	v_readlane_b32 s6, v255, 53
	v_readlane_b32 s7, v255, 54
	v_readlane_b32 s4, v255, 55
	v_readlane_b32 s5, v255, 56
	v_readlane_b32 s34, v255, 57
	v_readlane_b32 s35, v255, 58
	s_add_u32 s6, s6, 0x2bc8000
	s_addc_u32 s7, s7, 0
	s_lshl_b32 s8, s0, 27
	s_add_u32 s4, s4, s8
	s_addc_u32 s5, s5, 0
	s_add_u32 s34, s34, s8
	s_addc_u32 s35, s35, 0
	s_add_u32 s6, s6, s8
	s_addc_u32 s7, s7, 0
	s_lshl_b32 s30, s3, 14
	v_and_b32_e32 v120, 31, v200
	v_lshlrev_b32_e32 v2, 2, v120
	v_lshrrev_b32_e32 v3, 5, v200
	v_and_b32_e32 v4, 7, v200
	v_lshrrev_b32_e32 v6, 3, v200
	v_mul_u32_u24_e32 v7, 33, v3
	v_add_u32_e32 v7, v7, v120
	v_lshl_add_u32 v7, v7, 2, s30
	v_add_u32_e32 v8, 0x400, v7
	v_add_u32_e32 v9, 0x840, v7
	v_add_u32_e32 v10, 0xc40, v7
	v_add_u32_e32 v11, 0x1080, v7
	v_add_u32_e32 v12, 0x1480, v7
	v_add_u32_e32 v13, 0x18c0, v7
	v_add_u32_e32 v14, 0x1cc0, v7
	v_mul_u32_u24_e32 v120, 0x108, v4
	v_add_u32_e32 v120, v120, v6
	v_lshl_add_u32 v15, v120, 2, s30
	v_lshl_add_u32 v122, v3, 13, v2
	v_mov_b32_e32 v123, 0
	v_lshlrev_b32_e32 v124, 4, v4
	v_lshl_add_u32 v124, v6, 11, v124
	v_mov_b32_e32 v125, 0
	s_mov_b64 s[40:41], 0x20000
	s_mov_b64 s[42:43], 0x4000
	s_mov_b64 s[44:45], 0x4000
.Lsg_loop:
	s_lshr_b32 s8, s2, 11
	s_and_b32 s9, s2, 0x7ff
	s_lshr_b32 s10, s9, 7
	s_and_b32 s9, s9, 0x7f
	s_lshl_b32 s24, s10, 19
	s_lshr_b32 s25, s9, 3
	s_lshl_b32 s25, s25, 9
	s_add_i32 s24, s24, s25
	s_and_b32 s25, s9, 3
	s_lshl_b32 s25, s25, 7
	s_add_i32 s24, s24, s25
	s_lshr_b32 s29, s8, 9
	s_lshl_b32 s28, s8, 23
	s_add_u32 s28, s28, s24
	s_addc_u32 s29, s29, 0
	s_bitcmp0_b32 s9, 2
	s_cselect_b32 s24, s4, s34
	s_cselect_b32 s25, s5, s35
	s_add_u32 s28, s28, s24
	s_addc_u32 s29, s29, s25
	s_lshl_b32 s24, s9, 16
	s_lshl_b32 s25, s10, 7
	s_add_i32 s24, s24, s25
	s_lshr_b32 s11, s8, 9
	s_lshl_b32 s10, s8, 23
	s_add_u32 s10, s10, s24
	s_addc_u32 s11, s11, 0
	s_add_u32 s10, s10, s6
	s_addc_u32 s11, s11, s7
	v_lshl_add_u64 v[16:17], s[28:29], 0, v[122:123]
	v_lshl_add_u64 v[18:19], v[16:17], 0, s[44:45]
	v_lshl_add_u64 v[20:21], v[18:19], 0, s[44:45]
	v_lshl_add_u64 v[22:23], v[20:21], 0, s[44:45]
	v_lshl_add_u64 v[24:25], v[22:23], 0, s[44:45]
	v_lshl_add_u64 v[26:27], v[24:25], 0, s[44:45]
	v_lshl_add_u64 v[28:29], v[26:27], 0, s[44:45]
	v_lshl_add_u64 v[30:31], v[28:29], 0, s[44:45]
	global_load_dword v32, v[16:17], off nt
	global_load_dword v33, v[18:19], off nt
	global_load_dword v34, v[20:21], off nt
	global_load_dword v35, v[22:23], off nt
	global_load_dword v36, v[24:25], off nt
	global_load_dword v37, v[26:27], off nt
	global_load_dword v38, v[28:29], off nt
	global_load_dword v39, v[30:31], off nt
	v_lshl_add_u64 v[16:17], v[16:17], 0, s[40:41]
	v_lshl_add_u64 v[18:19], v[18:19], 0, s[40:41]
	v_lshl_add_u64 v[20:21], v[20:21], 0, s[40:41]
	v_lshl_add_u64 v[22:23], v[22:23], 0, s[40:41]
	v_lshl_add_u64 v[24:25], v[24:25], 0, s[40:41]
	v_lshl_add_u64 v[26:27], v[26:27], 0, s[40:41]
	v_lshl_add_u64 v[28:29], v[28:29], 0, s[40:41]
	v_lshl_add_u64 v[30:31], v[30:31], 0, s[40:41]
	global_load_dword v40, v[16:17], off nt
	global_load_dword v41, v[18:19], off nt
	global_load_dword v42, v[20:21], off nt
	global_load_dword v43, v[22:23], off nt
	global_load_dword v44, v[24:25], off nt
	global_load_dword v45, v[26:27], off nt
	global_load_dword v46, v[28:29], off nt
	global_load_dword v47, v[30:31], off nt
	v_lshl_add_u64 v[16:17], v[16:17], 0, s[40:41]
	v_lshl_add_u64 v[18:19], v[18:19], 0, s[40:41]
	v_lshl_add_u64 v[20:21], v[20:21], 0, s[40:41]
	v_lshl_add_u64 v[22:23], v[22:23], 0, s[40:41]
	v_lshl_add_u64 v[24:25], v[24:25], 0, s[40:41]
	v_lshl_add_u64 v[26:27], v[26:27], 0, s[40:41]
	v_lshl_add_u64 v[28:29], v[28:29], 0, s[40:41]
	v_lshl_add_u64 v[30:31], v[30:31], 0, s[40:41]
	global_load_dword v48, v[16:17], off nt
	global_load_dword v49, v[18:19], off nt
	global_load_dword v50, v[20:21], off nt
	global_load_dword v51, v[22:23], off nt
	global_load_dword v52, v[24:25], off nt
	global_load_dword v53, v[26:27], off nt
	global_load_dword v54, v[28:29], off nt
	global_load_dword v55, v[30:31], off nt
	v_lshl_add_u64 v[16:17], v[16:17], 0, s[40:41]
	v_lshl_add_u64 v[18:19], v[18:19], 0, s[40:41]
	v_lshl_add_u64 v[20:21], v[20:21], 0, s[40:41]
	v_lshl_add_u64 v[22:23], v[22:23], 0, s[40:41]
	v_lshl_add_u64 v[24:25], v[24:25], 0, s[40:41]
	v_lshl_add_u64 v[26:27], v[26:27], 0, s[40:41]
	v_lshl_add_u64 v[28:29], v[28:29], 0, s[40:41]
	v_lshl_add_u64 v[30:31], v[30:31], 0, s[40:41]
	global_load_dword v56, v[16:17], off nt
	global_load_dword v57, v[18:19], off nt
	global_load_dword v58, v[20:21], off nt
	global_load_dword v59, v[22:23], off nt
	global_load_dword v60, v[24:25], off nt
	global_load_dword v61, v[26:27], off nt
	global_load_dword v62, v[28:29], off nt
	global_load_dword v63, v[30:31], off nt
	v_lshl_add_u64 v[64:65], s[10:11], 0, v[124:125]
	v_lshl_add_u64 v[66:67], v[64:65], 0, s[42:43]
	v_lshl_add_u64 v[68:69], v[66:67], 0, s[42:43]
	v_lshl_add_u64 v[70:71], v[68:69], 0, s[42:43]
	s_waitcnt vmcnt(30)
; #define WAIT_VM(n) do {} while (0)
; #define WAIT_ALL() do {} while (0)
; #define WAVE_LDS_SYNC() do { int _z = 0; (void)emu::wave_xchg(&_z, 4); } while (0)
; #define LAUNDER_S(x) do {} while (0)
; #define LAS __attribute__((address_space(3)))
; #define WAIT_VM(n) asm volatile("s_waitcnt vmcnt(" #n ")" ::: "memory")
; #define WAIT_ALL() asm volatile("s_waitcnt vmcnt(0) lgkmcnt(0)" ::: "memory")
; #define WAVE_LDS_SYNC() asm volatile("s_waitcnt lgkmcnt(0)" ::: "memory")
; #define NT_LOAD(p) __builtin_nontemporal_load(p)
; #define NT_STORE(v, p) __builtin_nontemporal_store((v), (p))
; #define LAUNDER_S(x) asm volatile("" : "+s"(x))
; DEV int lane_id() { return (int)__builtin_amdgcn_mbcnt_hi(~0u, __builtin_amdgcn_mbcnt_lo(~0u, 0u)); }
; DEV unsigned pk2(float lo, float hi) { return f2bf(lo) | (f2bf(hi) << 16); }
; DEV unsigned pk2(float lo, float hi) { const f32x2n_t v = {lo, hi}; return __builtin_bit_cast(unsigned, __builtin_convertvector(v, bf16x2n_t)); }
; DEV void xcd_barrier(const XcdBarrier& b) {
;     WAIT_VM(0);
;     __syncthreads();
;     int bw = b.wave; LAUNDER_S(bw);
;     if (bw == 0 && lane_id() == 0) {
;         unsigned* bar = b.bar; LAUNDER_S(bar);
;         unsigned bx = b.x; LAUNDER_S(bx);
;         WAIT_ALL();
;         unsigned nloc = b.st[0], nx = b.st[1];
; DEV void tr_item(const float* W, int ldw, int col0, int k0, bf16_t* WT, int K, int row0, LAS float* scr, int lane) {
; #pragma unroll 8
;     for (int i = 0; i < 32; ++i) { const int kk = 2 * i + (lane >> 5); scr[kk * 33 + (lane & 31)] = NT_LOAD(&W[(size_t)(k0 + kk) * ldw + col0 + (lane & 31)]); }
;     WAVE_LDS_SYNC();
;     const int c = lane & 7;
; #pragma unroll
;     for (int j = 0; j < 4; ++j) { const int n = (lane >> 3) + 8 * j; const LAS float* s = scr + (8 * c) * 33 + n;
;         u32x4 o; o.x = pk2(s[0 * 33], s[1 * 33]); o.y = pk2(s[2 * 33], s[3 * 33]); o.z = pk2(s[4 * 33], s[5 * 33]); o.w = pk2(s[6 * 33], s[7 * 33]);
;         NT_STORE(o, (u32x4*)(WT + (size_t)(row0 + n) * K + k0 + 8 * c)); }
;     WAVE_LDS_SYNC();
	ds_write2_b32 v7, v32, v33 offset1:66
	s_waitcnt vmcnt(28)
	ds_write2_b32 v7, v34, v35 offset0:132 offset1:198
	s_waitcnt vmcnt(26)
	ds_write2_b32 v8, v36, v37 offset0:8 offset1:74
	s_waitcnt vmcnt(24)
	ds_write2_b32 v8, v38, v39 offset0:140 offset1:206
	s_waitcnt vmcnt(22)
	ds_write2_b32 v9, v40, v41 offset1:66
	s_waitcnt vmcnt(20)
	ds_write2_b32 v9, v42, v43 offset0:132 offset1:198
	s_waitcnt vmcnt(18)
	ds_write2_b32 v10, v44, v45 offset0:8 offset1:74
	s_waitcnt vmcnt(16)
	ds_write2_b32 v10, v46, v47 offset0:140 offset1:206
	s_waitcnt vmcnt(14)
	ds_write2_b32 v11, v48, v49 offset1:66
	s_waitcnt vmcnt(12)
	ds_write2_b32 v11, v50, v51 offset0:132 offset1:198
	s_waitcnt vmcnt(10)
	ds_write2_b32 v12, v52, v53 offset0:8 offset1:74
	s_waitcnt vmcnt(8)
	ds_write2_b32 v12, v54, v55 offset0:140 offset1:206
	s_waitcnt vmcnt(6)
	ds_write2_b32 v13, v56, v57 offset1:66
	s_waitcnt vmcnt(4)
	ds_write2_b32 v13, v58, v59 offset0:132 offset1:198
	s_waitcnt vmcnt(2)
	ds_write2_b32 v14, v60, v61 offset0:8 offset1:74
	s_waitcnt vmcnt(0)
	ds_write2_b32 v14, v62, v63 offset0:140 offset1:206
	ds_read2_b32 v[72:73], v15 offset1:8
	ds_read2_b32 v[74:75], v15 offset0:33 offset1:41
	ds_read2_b32 v[76:77], v15 offset0:66 offset1:74
	ds_read2_b32 v[78:79], v15 offset0:99 offset1:107
	ds_read2_b32 v[80:81], v15 offset0:132 offset1:140
	ds_read2_b32 v[82:83], v15 offset0:165 offset1:173
	ds_read2_b32 v[84:85], v15 offset0:198 offset1:206
	ds_read2_b32 v[86:87], v15 offset0:231 offset1:239
	ds_read2_b32 v[88:89], v15 offset0:16 offset1:24
	ds_read2_b32 v[90:91], v15 offset0:49 offset1:57
	ds_read2_b32 v[92:93], v15 offset0:82 offset1:90
	ds_read2_b32 v[94:95], v15 offset0:115 offset1:123
	s_waitcnt lgkmcnt(4)
	v_cvt_pk_bf16_f32 v104, v72, v74
	v_cvt_pk_bf16_f32 v105, v76, v78
	v_cvt_pk_bf16_f32 v106, v80, v82
	v_cvt_pk_bf16_f32 v107, v84, v86
	v_cvt_pk_bf16_f32 v108, v73, v75
	v_cvt_pk_bf16_f32 v109, v77, v79
	v_cvt_pk_bf16_f32 v110, v81, v83
	v_cvt_pk_bf16_f32 v111, v85, v87
	ds_read2_b32 v[96:97], v15 offset0:148 offset1:156
	ds_read2_b32 v[98:99], v15 offset0:181 offset1:189
	ds_read2_b32 v[100:101], v15 offset0:214 offset1:222
	ds_read2_b32 v[102:103], v15 offset0:247 offset1:255
	global_store_dwordx4 v[64:65], v[104:107], off nt
	global_store_dwordx4 v[66:67], v[108:111], off nt
	s_waitcnt lgkmcnt(0)
	v_cvt_pk_bf16_f32 v112, v88, v90
	v_cvt_pk_bf16_f32 v113, v92, v94
	v_cvt_pk_bf16_f32 v114, v96, v98
	v_cvt_pk_bf16_f32 v115, v100, v102
	v_cvt_pk_bf16_f32 v116, v89, v91
	v_cvt_pk_bf16_f32 v117, v93, v95
	v_cvt_pk_bf16_f32 v118, v97, v99
	v_cvt_pk_bf16_f32 v119, v101, v103
	global_store_dwordx4 v[68:69], v[112:115], off nt
	global_store_dwordx4 v[70:71], v[116:119], off nt
	s_addk_i32 s2, 0x780
	s_cmp_lt_u32 s2, 0x2580
	s_cbranch_scc1 .Lsg_loop
.Lsg_done:
.LBB0_1333:
	s_waitcnt vmcnt(0)
	v_readlane_b32 s0, v251, 29
	s_waitcnt vmcnt(0)
	s_barrier
	s_nop 0
	v_or_b32_e32 v0, s0, v200
	v_cmp_eq_u32_e32 vcc, 0, v0
	s_and_saveexec_b64 s[34:35], vcc
	s_cbranch_execz .LBB0_1377
	v_readlane_b32 s4, v251, 0
	v_readlane_b32 s6, v251, 2
	v_readlane_b32 s7, v251, 3
	s_mov_b64 s[36:37], s[6:7]
	v_readlane_b32 s0, v251, 28
	v_readlane_b32 s2, v253, 7
	s_waitcnt vmcnt(0) lgkmcnt(0)
	v_readlane_b32 s5, v251, 1
	s_nop 0
	v_mov_b32_e32 v0, s2
	ds_read_b32 v2, v0
	v_readlane_b32 s2, v253, 8
	s_waitcnt lgkmcnt(0)
	v_cmp_ne_u32_e32 vcc, 0, v2
	v_mov_b32_e32 v0, s2
	ds_read_b32 v0, v0
	s_cbranch_vccnz .LBB0_1348
	s_add_u32 s2, s36, 0x1000
	s_addc_u32 s3, s37, 0
	s_add_u32 s4, s36, 0x1100
	s_addc_u32 s5, s37, 0
	s_add_u32 s6, s36, 0x1200
	s_addc_u32 s7, s37, 0
	s_add_u32 s8, s36, 0x1300
	s_addc_u32 s9, s37, 0
	s_mov_b32 s28, 1
	s_mov_b64 s[10:11], 0
	s_branch .LBB0_1338

; #define LAS __attribute__((address_space(3)))
; #define NT_LOAD(p) __builtin_nontemporal_load(p)
; DEV void tr_item(const float* W, int ldw, int col0, int k0, bf16_t* WT, int K, int row0, LAS float* scr, int lane) {
; #pragma unroll 8
;     for (int i = 0; i < 32; ++i) { const int kk = 2 * i + (lane >> 5); scr[kk * 33 + (lane & 31)] = NT_LOAD(&W[(size_t)(k0 + kk) * ldw + col0 + (lane & 31)]); }
; DEV void phase_prologue_a(const Frame& F0) {
;     ...
;         constexpr int D_ITEMS = (FF / 64) * 32;
;         for (int it = F.gw; it < NE * D_ITEMS; it += F.NGW) { const int e = it / D_ITEMS, r = it % D_ITEMS, kb = r / 32, nb = r % 32;
;             tr_item(GIN(I_WDOWN) + ((size_t)l * NE + e) * FF * 1024, 1024, 32 * nb, 64 * kb, (bf16_t*)(F.ws + WS_WD) + ((size_t)l * NE + e) * 1024 * FF, FF, 32 * nb, scr, F.lane); }
.LBB0_1828:
	s_waitcnt vmcnt(0)
	s_mov_b64 s[52:53], 0x1000
	v_readlane_b32 s48, v253, 49
	s_barrier
	v_readlane_b32 s3, v255, 52
	s_add_i32 s0, s3, 1
	v_writelane_b32 v255, s0, 52
	s_cmp_gt_u32 s0, 3
	s_cbranch_scc1 .Lsd_done
	v_readlane_b32 s2, v255, 51
	s_cmp_lg_u32 s2, 0x100
	s_cbranch_scc1 .Lsd_done
	v_readlane_b32 s2, v255, 48
	s_cmp_lt_u32 s2, 64
	s_cbranch_scc1 .Lsd_done
	v_readlane_b32 s3, v251, 29
	s_sub_i32 s2, s2, 64
	s_lshl_b32 s2, s2, 3
	s_add_i32 s2, s2, s3
	v_readlane_b32 s6, v255, 53
	v_readlane_b32 s7, v255, 54
	v_readlane_b32 s4, v255, 49
	v_readlane_b32 s5, v255, 50
	s_add_u32 s6, s6, 0x22bc8000
	s_addc_u32 s7, s7, 0
	s_lshl_b32 s8, s0, 27
	s_add_u32 s4, s4, s8
	s_addc_u32 s5, s5, 0
	s_lshl_b32 s8, s0, 26
	s_add_u32 s6, s6, s8
	s_addc_u32 s7, s7, 0
	s_lshl_b32 s30, s3, 14
	v_and_b32_e32 v120, 31, v200
	v_lshlrev_b32_e32 v2, 2, v120
	v_lshrrev_b32_e32 v3, 5, v200
	v_and_b32_e32 v4, 7, v200
	v_lshrrev_b32_e32 v6, 3, v200
	v_mul_u32_u24_e32 v7, 33, v3
	v_add_u32_e32 v7, v7, v120
	v_lshl_add_u32 v7, v7, 2, s30
	v_add_u32_e32 v8, 0x400, v7
	v_add_u32_e32 v9, 0x840, v7
	v_add_u32_e32 v10, 0xc40, v7
	v_add_u32_e32 v11, 0x1080, v7
	v_add_u32_e32 v12, 0x1480, v7
	v_add_u32_e32 v13, 0x18c0, v7
	v_add_u32_e32 v14, 0x1cc0, v7
	v_mul_u32_u24_e32 v120, 0x108, v4
	v_add_u32_e32 v120, v120, v6
	v_lshl_add_u32 v15, v120, 2, s30
	v_lshl_add_u32 v122, v3, 12, v2
	v_mov_b32_e32 v123, 0
	v_lshlrev_b32_e32 v124, 4, v4
	v_lshl_add_u32 v124, v6, 12, v124
	v_mov_b32_e32 v125, 0
	s_mov_b64 s[40:41], 0x10000
	s_mov_b64 s[42:43], 0x8000
	s_mov_b64 s[44:45], 0x2000
